# scan finisher: quad sum of squares by DPP adds instead of two ds_bpermute round trips
# speedup vs baseline: 1.0188x; 1.0188x over previous
; #define LAS __attribute__((address_space(3)))
; __device__ __forceinline__ unsigned pk2(float lo, float hi) { return pg8::cvt_pk_bf16_v(lo, hi); }
; __device__ __forceinline__ float siluf(float x) { return x * __builtin_amdgcn_rcpf(1.0f + __expf(-x)); }
; __device__ __forceinline__ void unpack8(v4u w, float (&f)[8]) { f[0] = bflo(w.x); f[1] = bfhi(w.x); f[2] = bflo(w.y); f[3] = bfhi(w.y); f[4] = bflo(w.z); f[5] = bfhi(w.z); f[6] = bflo(w.w); f[7] = bfhi(w.w); }
; __device__ __forceinline__ void scan_prompt_wg(const Params& P, LAS unsigned char* lds, int s, int h, int wave, int lane) {
;     ...
;             if (n >= 1) {
;                 const LAS unsigned char* ot = lds + (((n - 1) & 1) ? OT_B : OT_A) + ft * 128 + fp * 32;
;                 const LAS unsigned char* zt = lds + ZT_OFF + ((n - 1) & 1) * 8192 + ft * 128 + fp * 32;
;                 float o[16], zf[16]; { float t0[8], t1[8]; unpack8(*(const LAS v4u*)ot, t0); unpack8(*(const LAS v4u*)(ot + 16), t1);
; #pragma unroll
;                     for (int i = 0; i < 8; ++i) { o[i] = t0[i]; o[8 + i] = t1[i]; }
;                     unpack8(*(const LAS v4u*)zt, t0); unpack8(*(const LAS v4u*)(zt + 16), t1);
; #pragma unroll
;                     for (int i = 0; i < 8; ++i) { zf[i] = t0[i]; zf[8 + i] = t1[i]; } }
;                 float ss = 0.f;
; #pragma unroll
;                 for (int i = 0; i < 16; ++i) ss += o[i] * o[i];
;                 ss += __shfl_xor(ss, 1); ss += __shfl_xor(ss, 2);
;                 const float rstd = __builtin_amdgcn_rsqf(ss * (1.0f / 64.0f) + 1e-6f);
;                 float r[16];
; #pragma unroll
;                 for (int i = 0; i < 16; ++i) r[i] = o[i] * rstd * gg[i] * siluf(zf[i]);
;                 bf16* mp = Mr + (size_t)(n - 1) * 64 * 1024;
;                 v4u w0, w1; w0.x = pk2(r[0], r[1]); w0.y = pk2(r[2], r[3]); w0.z = pk2(r[4], r[5]); w0.w = pk2(r[6], r[7]); w1.x = pk2(r[8], r[9]); w1.y = pk2(r[10], r[11]); w1.z = pk2(r[12], r[13]); w1.w = pk2(r[14], r[15]);
;                 *(v4u*)mp = w0; *(v4u*)(mp + 8) = w1;
;             }
.LBB0_666:
	v_add_co_u32_e64 v25, s[38:39], s10, 1
	s_nop 0
	v_readfirstlane_b32 s45, v25
	s_and_b64 vcc, exec, s[38:39]
	s_cbranch_vccnz .LBB0_668
	s_and_b32 s20, s10, 1
	v_lshl_add_u32 v25, s20, 13, v27
	ds_read_b128 v[28:31], v25 offset:16
	s_cmp_eq_u32 s20, 0
	s_cselect_b32 s20, s44, 0x20200
	v_add_u32_e32 v32, s20, v26
	ds_read_b128 v[36:39], v32 offset:16
	s_waitcnt lgkmcnt(1)
	v_lshlrev_b32_e32 v34, 16, v31
	v_mul_f32_e32 v33, 0xbfb8aa3b, v34
	v_exp_f32_e32 v48, v33
	ds_read_b128 v[40:43], v25
	ds_read_b128 v[44:47], v32
	v_lshlrev_b32_e32 v62, 16, v29
	s_waitcnt lgkmcnt(2)
	v_lshlrev_b32_e32 v49, 16, v38
	v_add_f32_e32 v25, 1.0, v48
	v_rcp_f32_e32 v25, v25
	v_and_b32_e32 v48, 0xffff0000, v38
	v_and_b32_e32 v63, 0xffff0000, v29
	v_mul_f32_e32 v29, 0xbfb8aa3b, v63
	v_mul_f32_e32 v38, v25, v34
	v_mul_f32_e32 v25, 0xbfb8aa3b, v62
	v_exp_f32_e32 v25, v25
	v_exp_f32_e32 v29, v29
	v_lshlrev_b32_e32 v68, 16, v37
	v_and_b32_e32 v69, 0xffff0000, v37
	v_add_f32_e32 v25, 1.0, v25
	v_rcp_f32_e32 v66, v25
	v_add_f32_e32 v25, 1.0, v29
	v_rcp_f32_e32 v67, v25
	v_and_b32_e32 v37, 0xffff0000, v28
	v_and_b32_e32 v60, 0xffff0000, v31
	s_waitcnt lgkmcnt(1)
	v_lshlrev_b32_e32 v74, 16, v43
	v_pk_mul_f32 v[62:63], v[66:67], v[62:63]
	v_lshlrev_b32_e32 v66, 16, v36
	v_and_b32_e32 v67, 0xffff0000, v36
	v_lshlrev_b32_e32 v36, 16, v28
	v_mul_f32_e32 v25, 0xbfb8aa3b, v36
	v_exp_f32_e32 v25, v25
	v_mul_f32_e32 v28, 0xbfb8aa3b, v37
	v_exp_f32_e32 v31, v28
	v_and_b32_e32 v75, 0xffff0000, v43
	v_add_f32_e32 v25, 1.0, v25
	v_rcp_f32_e32 v72, v25
	v_add_f32_e32 v25, 1.0, v31
	v_rcp_f32_e32 v73, v25
	v_mul_f32_e32 v25, 0xbfb8aa3b, v74
	v_exp_f32_e32 v25, v25
	v_mul_f32_e32 v31, 0xbfb8aa3b, v75
	v_exp_f32_e32 v31, v31
	v_pk_mul_f32 v[36:37], v[72:73], v[36:37]
	v_add_f32_e32 v25, 1.0, v25
	v_rcp_f32_e32 v72, v25
	v_add_f32_e32 v25, 1.0, v31
	v_rcp_f32_e32 v73, v25
	s_waitcnt lgkmcnt(0)
	v_lshlrev_b32_e32 v76, 16, v47
	v_and_b32_e32 v77, 0xffff0000, v47
	v_and_b32_e32 v47, 0xffff0000, v42
	v_pk_mul_f32 v[72:73], v[72:73], v[74:75]
	v_lshlrev_b32_e32 v74, 16, v46
	v_and_b32_e32 v75, 0xffff0000, v46
	v_lshlrev_b32_e32 v46, 16, v42
	v_mul_f32_e32 v25, 0xbfb8aa3b, v46
	v_exp_f32_e32 v25, v25
	v_mul_f32_e32 v31, 0xbfb8aa3b, v47
	v_exp_f32_e32 v31, v31
	v_lshlrev_b32_e32 v84, 16, v41
	v_add_f32_e32 v25, 1.0, v25
	v_rcp_f32_e32 v80, v25
	v_add_f32_e32 v25, 1.0, v31
	v_rcp_f32_e32 v81, v25
	v_and_b32_e32 v85, 0xffff0000, v41
	v_mul_f32_e32 v25, 0xbfb8aa3b, v84
	v_exp_f32_e32 v25, v25
	v_mul_f32_e32 v31, 0xbfb8aa3b, v85
	v_exp_f32_e32 v31, v31
	v_lshlrev_b32_e32 v90, 16, v44
	v_add_f32_e32 v25, 1.0, v25
	v_and_b32_e32 v91, 0xffff0000, v44
	v_lshlrev_b32_e32 v82, 16, v45
	v_and_b32_e32 v83, 0xffff0000, v45
	v_rcp_f32_e32 v88, v25
	v_add_f32_e32 v25, 1.0, v31
	v_lshlrev_b32_e32 v44, 16, v40
	v_and_b32_e32 v45, 0xffff0000, v40
	v_pk_mul_f32 v[40:41], v[90:91], v[90:91]
	v_pk_mul_f32 v[86:87], v[82:83], v[82:83]
	v_rcp_f32_e32 v89, v25
	v_add_f32_e32 v25, v40, v41
	v_add_f32_e32 v25, v86, v25
	v_pk_mul_f32 v[42:43], v[74:75], v[74:75]
	v_add_f32_e32 v25, v87, v25
	v_add_f32_e32 v25, v42, v25
	v_pk_mul_f32 v[78:79], v[76:77], v[76:77]
	v_add_f32_e32 v25, v43, v25
	v_add_f32_e32 v25, v78, v25
	v_pk_mul_f32 v[28:29], v[66:67], v[66:67]
	v_add_f32_e32 v25, v79, v25
	v_add_f32_e32 v25, v28, v25
	v_pk_mul_f32 v[70:71], v[68:69], v[68:69]
	v_add_f32_e32 v25, v29, v25
	v_add_f32_e32 v25, v70, v25
	v_pk_mul_f32 v[50:51], v[48:49], v[48:49]
	v_and_b32_e32 v61, 0xffff0000, v39
	v_add_f32_e32 v25, v71, v25
	v_lshlrev_b32_e32 v33, 16, v39
	v_mov_b32_e32 v32, v61
	v_add_f32_e32 v25, v51, v25
	v_pk_mul_f32 v[64:65], v[32:33], v[32:33]
	v_add_f32_e32 v25, v50, v25
	v_add_f32_e32 v25, v65, v25
	v_add_f32_e32 v25, v64, v25
	v_lshlrev_b32_e32 v50, 16, v30
	v_and_b32_e32 v51, 0xffff0000, v30
	v_mul_f32_e32 v29, 0xbfb8aa3b, v44
	v_mul_f32_e32 v31, 0xbfb8aa3b, v45
	v_add_f32_dpp v25, v25, v25 quad_perm:[1,0,3,2] row_mask:0xf bank_mask:0xf
	v_mul_f32_e32 v30, 0xbfb8aa3b, v51
	v_exp_f32_e32 v29, v29
	v_exp_f32_e32 v31, v31
	v_exp_f32_e32 v34, v30
	v_add_f32_dpp v25, v25, v25 quad_perm:[2,3,0,1] row_mask:0xf bank_mask:0xf
	v_fmamk_f32 v25, v25, 0x3c800000, v24
	v_rsq_f32_e32 v32, v25
	v_mul_f32_e32 v25, 0xbfb8aa3b, v50
	v_exp_f32_e32 v25, v25
	v_pk_mul_f32 v[40:41], v[80:81], v[46:47]
	v_pk_mul_f32 v[46:47], v[32:33], v[66:67] op_sel_hi:[0,1]
	v_pk_mul_f32 v[46:47], v[10:11], v[46:47]
	v_add_f32_e32 v25, 1.0, v25
	v_pk_mul_f32 v[36:37], v[36:37], v[46:47]
	v_pk_mul_f32 v[46:47], v[32:33], v[68:69] op_sel_hi:[0,1]
	v_add_f32_e32 v28, 1.0, v29
	v_add_f32_e32 v29, 1.0, v31
	v_pk_mul_f32 v[30:31], v[12:13], v[46:47]
	v_rcp_f32_e32 v46, v25
	v_add_f32_e32 v25, 1.0, v34
	v_rcp_f32_e32 v28, v28
	v_rcp_f32_e32 v29, v29
	v_rcp_f32_e32 v47, v25
	v_mul_f32_e32 v25, 0xbfb8aa3b, v60
	v_exp_f32_e32 v25, v25
	v_pk_mul_f32 v[28:29], v[28:29], v[44:45]
	v_pk_mul_f32 v[44:45], v[32:33], v[90:91] op_sel_hi:[0,1]
	v_pk_mul_f32 v[44:45], v[2:3], v[44:45]
	v_add_f32_e32 v25, 1.0, v25
	v_pk_mul_f32 v[28:29], v[28:29], v[44:45]
	v_pk_mul_f32 v[44:45], v[32:33], v[82:83] op_sel_hi:[0,1]
	v_pk_mul_f32 v[62:63], v[62:63], v[30:31]
	v_pk_mul_f32 v[30:31], v[46:47], v[50:51]
	v_pk_mul_f32 v[46:47], v[32:33], v[48:49] op_sel_hi:[0,1]
	v_rcp_f32_e32 v48, v25
	v_pk_mul_f32 v[42:43], v[88:89], v[84:85]
	v_pk_mul_f32 v[44:45], v[4:5], v[44:45]
	v_pk_mul_f32 v[46:47], v[20:21], v[46:47]
	v_pk_mul_f32 v[42:43], v[42:43], v[44:45]
	v_pk_mul_f32 v[44:45], v[32:33], v[74:75] op_sel_hi:[0,1]
	v_pk_mul_f32 v[44:45], v[6:7], v[44:45]
	v_mov_b32_e32 v49, v32
	v_pk_mul_f32 v[40:41], v[40:41], v[44:45]
	v_pk_mul_f32 v[44:45], v[32:33], v[76:77] op_sel_hi:[0,1]
	v_pk_mul_f32 v[46:47], v[30:31], v[46:47] op_sel:[0,1] op_sel_hi:[1,0]
	v_mul_f32_e32 v30, v32, v33
	v_pk_mul_f32 v[32:33], v[48:49], v[60:61]
	v_pk_mul_f32 v[44:45], v[8:9], v[44:45]
	v_mov_b32_e32 v31, v33
	s_lshl_b64 s[20:21], s[10:11], 17
	v_pk_mul_f32 v[44:45], v[72:73], v[44:45]
	v_pk_mul_f32 v[30:31], v[16:17], v[30:31]
	v_mov_b32_e32 v39, v32
	s_cmpk_lg_i32 s10, 0x7f
	v_pk_mul_f32 v[32:33], v[38:39], v[30:31]
	v_lshl_add_u64 v[48:49], v[14:15], 0, s[20:21]
	v_readlane_b32 s96, v247, 24
	v_cvt_pk_bf16_f32 v28, v28, v29
	v_cvt_pk_bf16_f32 v29, v42, v43
	v_cvt_pk_bf16_f32 v30, v40, v41
	v_cvt_pk_bf16_f32 v31, v44, v45
	s_cselect_b64 s[38:39], -1, 0
	v_cvt_pk_bf16_f32 v36, v36, v37
	v_cvt_pk_bf16_f32 v37, v62, v63
	v_cvt_pk_bf16_f32 v38, v46, v47
	v_cvt_pk_bf16_f32 v39, v32, v33
	global_store_dwordx4 v[48:49], v[28:31], off
	global_store_dwordx4 v[48:49], v[36:39], off offset:16
